# MoE per-tile latency: batch the 4 gate loads in the stage-1 epilogue, issue cnt and rowlist loads together in the tile prologue
# speedup vs baseline: 1.0211x; 1.0211x over previous
; template <int STAGE>
; __device__ void phase_moe(const Params& p, u16* smem) {
;     ...
;     for (int q = 0; q < nex; q++) if (sPref[q + 1] <= mg) eq = q + 1;
;     int mt = mg - sPref[eq];
;     const int e = xg + ngrp * eq;
;     int ce = p.cnt()[e * 32];
;     if (t < 128) {
;       int idx = mt * 128 + t;
;       int a = idx < ce ? p.rowlist()[e * SEQ + idx] : -1;
;       sAsg[t] = a;
;       sArow[t] = a < 0 ? 0 : (STAGE == 0 ? (a >> 1) : a);
;     }
.LBB0_886:
	v_max_i32_e32 v0, v0, v1
	v_cmp_ne_u32_e32 vcc, s20, v0
	s_nop 1
	v_cndmask_b32_e32 v1, 0, v0, vcc
	v_lshlrev_b32_e32 v0, s2, v1
	v_add_u32_e32 v0, s52, v0
	s_and_saveexec_b64 s[0:1], s[6:7]
	s_cbranch_execz .LBB0_890
	v_lshlrev_b32_e32 v2, 5, v0
	v_ashrrev_i32_e32 v3, 31, v2
	v_lshlrev_b64 v[2:3], 2, v[2:3]
	v_lshl_add_u64 v[2:3], s[14:15], 0, v[2:3]
	global_load_dword v3, v[2:3], off
	v_lshlrev_b32_e32 v1, 2, v1
	v_add_u32_e32 v1, 0x110, v1
	v_add_u32_e32 v1, 0x10000, v1
	ds_read_b32 v1, v1
	s_waitcnt lgkmcnt(0)
	v_sub_u32_e32 v1, s34, v1
	v_lshl_or_b32 v2, v1, 7, v128
	v_lshl_add_u32 v4, v0, 13, v2
	v_ashrrev_i32_e32 v5, 31, v4
	v_lshl_add_u64 v[4:5], v[4:5], 2, s[16:17]
	global_load_dword v4, v[4:5], off
	s_waitcnt vmcnt(0)
	v_cmp_lt_i32_e32 vcc, v2, v3
	s_nop 1
	v_cndmask_b32_e32 v1, -1, v4, vcc
	ds_write_b32 v182, v1
	v_max_i32_e32 v1, 0, v1
	v_lshrrev_b32_e32 v1, 1, v1
	ds_write_b32 v183, v1

; template <int STAGE>
; __device__ void phase_moe(const Params& p, u16* smem) {
;     ...
;     for (int q = 0; q < nex; q++) if (sPref[q + 1] <= mg) eq = q + 1;
;     int mt = mg - sPref[eq];
;     const int e = xg + ngrp * eq;
;     int ce = p.cnt()[e * 32];
;     if (t < 128) {
;       int idx = mt * 128 + t;
;       int a = idx < ce ? p.rowlist()[e * SEQ + idx] : -1;
;       sAsg[t] = a;
;       sArow[t] = a < 0 ? 0 : (STAGE == 0 ? (a >> 1) : a);
;     }
.LBB0_976:
	v_max_i32_e32 v0, v0, v1
	v_cmp_ne_u32_e32 vcc, s22, v0
	s_nop 1
	v_cndmask_b32_e32 v1, 0, v0, vcc
	v_lshlrev_b32_e32 v0, s3, v1
	v_add_u32_e32 v0, s52, v0
	s_and_saveexec_b64 s[0:1], s[6:7]
	s_cbranch_execz .LBB0_980
	v_lshlrev_b32_e32 v2, 5, v0
	v_ashrrev_i32_e32 v3, 31, v2
	v_lshlrev_b64 v[2:3], 2, v[2:3]
	v_lshl_add_u64 v[2:3], s[14:15], 0, v[2:3]
	global_load_dword v3, v[2:3], off
	v_lshlrev_b32_e32 v1, 2, v1
	v_add_u32_e32 v1, 0x110, v1
	v_add_u32_e32 v1, 0x10000, v1
	ds_read_b32 v1, v1
	s_waitcnt lgkmcnt(0)
	v_sub_u32_e32 v1, s36, v1
	v_lshl_or_b32 v2, v1, 7, v128
	v_lshl_add_u32 v4, v0, 13, v2
	v_ashrrev_i32_e32 v5, 31, v4
	v_lshl_add_u64 v[4:5], v[4:5], 2, s[16:17]
	global_load_dword v4, v[4:5], off
	s_waitcnt vmcnt(0)
	v_cmp_lt_i32_e32 vcc, v2, v3
	s_nop 1
	v_cndmask_b32_e32 v1, -1, v4, vcc
	ds_write_b32 v137, v1
	v_max_i32_e32 v1, 0, v1
	ds_write_b32 v158, v1

; template <int STAGE>
; __device__ void phase_moe(const Params& p, u16* smem) {
;     ...
;                 [&](int m, int nb, f32x4 (&a)[4]) {
;                   int as = sAsg[m];
;                   if (as >= 0) {
;                     float gt = gp[as];
; #pragma unroll
;                     for (int q = 0; q < 4; q++) store_bf4(yp + (long)as * DM + nb + q * 16, gt * a[q][0], gt * a[q][1], gt * a[q][2], gt * a[q][3]);
;                   }
;                 });
.LBB0_992:
	ds_read_b32 v20, v133
	ds_read_b32 v21, v133 offset:64
	ds_read_b32 v22, v133 offset:128
	ds_read_b32 v23, v133 offset:192
	s_lshl_b64 s[0:1], s[0:1], 1
	s_add_u32 s0, s76, s0
	s_addc_u32 s1, s77, s1
	v_lshlrev_b32_e32 v0, 1, v136
	s_waitcnt lgkmcnt(0)
	v_mov_b32_e32 v3, v131
	v_max_i32_e32 v2, 0, v20
	v_lshl_add_u64 v[4:5], v[2:3], 2, s[18:19]
	global_load_dword v24, v[4:5], off
	v_max_i32_e32 v2, 0, v21
	v_lshl_add_u64 v[4:5], v[2:3], 2, s[18:19]
	global_load_dword v25, v[4:5], off
	v_max_i32_e32 v2, 0, v22
	v_lshl_add_u64 v[4:5], v[2:3], 2, s[18:19]
	global_load_dword v26, v[4:5], off
	v_max_i32_e32 v2, 0, v23
	v_lshl_add_u64 v[4:5], v[2:3], 2, s[18:19]
	global_load_dword v27, v[4:5], off
	s_waitcnt vmcnt(0)
	v_cmp_lt_i32_e32 vcc, -1, v20
	s_and_saveexec_b64 s[34:35], vcc
	s_cbranch_execz .LBB0_994
	v_mov_b32_e32 v2, v20
	v_mov_b32_e32 v3, v131
	v_lshlrev_b64 v[2:3], 12, v[2:3]
	v_mov_b32_e32 v1, v131
	v_lshl_add_u64 v[2:3], s[0:1], 0, v[2:3]
	v_lshl_add_u64 v[2:3], v[2:3], 0, v[0:1]
	v_mov_b32_e32 v4, v24
	v_pk_mul_f32 v[6:7], v[124:125], v[4:5] op_sel_hi:[1,0]
	v_pk_mul_f32 v[8:9], v[126:127], v[4:5] op_sel_hi:[1,0]
	v_pk_mul_f32 v[10:11], v[120:121], v[4:5] op_sel_hi:[1,0]
	v_pk_mul_f32 v[12:13], v[122:123], v[4:5] op_sel_hi:[1,0]
	v_pk_mul_f32 v[14:15], v[116:117], v[4:5] op_sel_hi:[1,0]
	v_pk_mul_f32 v[16:17], v[118:119], v[4:5] op_sel_hi:[1,0]
	v_pk_mul_f32 v[18:19], v[112:113], v[4:5] op_sel_hi:[1,0]
	v_pk_mul_f32 v[4:5], v[114:115], v[4:5] op_sel_hi:[1,0]
	v_cvt_pk_bf16_f32 v6, v6, v7
	v_cvt_pk_bf16_f32 v7, v8, v9
	v_cvt_pk_bf16_f32 v8, v10, v11
	v_cvt_pk_bf16_f32 v9, v12, v13
	v_cvt_pk_bf16_f32 v10, v14, v15
	v_cvt_pk_bf16_f32 v11, v16, v17
	v_cvt_pk_bf16_f32 v12, v18, v19
	v_cvt_pk_bf16_f32 v13, v4, v5
	global_store_dwordx2 v[2:3], v[6:7], off
	global_store_dwordx2 v[2:3], v[8:9], off offset:32
	global_store_dwordx2 v[2:3], v[10:11], off offset:64
	global_store_dwordx2 v[2:3], v[12:13], off offset:96
.LBB0_994:
	s_or_b64 exec, exec, s[34:35]
	v_cmp_lt_i32_e32 vcc, -1, v21
	s_and_saveexec_b64 s[34:35], vcc
	s_cbranch_execz .LBB0_996
	v_mov_b32_e32 v2, v21
	v_mov_b32_e32 v3, v131
	v_lshlrev_b64 v[2:3], 12, v[2:3]
	v_mov_b32_e32 v1, v131
	v_lshl_add_u64 v[2:3], s[0:1], 0, v[2:3]
	v_lshl_add_u64 v[2:3], v[2:3], 0, v[0:1]
	v_mov_b32_e32 v4, v25
	v_pk_mul_f32 v[6:7], v[108:109], v[4:5] op_sel_hi:[1,0]
	v_pk_mul_f32 v[8:9], v[110:111], v[4:5] op_sel_hi:[1,0]
	v_pk_mul_f32 v[10:11], v[104:105], v[4:5] op_sel_hi:[1,0]
	v_pk_mul_f32 v[12:13], v[106:107], v[4:5] op_sel_hi:[1,0]
	v_pk_mul_f32 v[14:15], v[100:101], v[4:5] op_sel_hi:[1,0]
	v_pk_mul_f32 v[16:17], v[102:103], v[4:5] op_sel_hi:[1,0]
	v_pk_mul_f32 v[18:19], v[96:97], v[4:5] op_sel_hi:[1,0]
	v_pk_mul_f32 v[4:5], v[98:99], v[4:5] op_sel_hi:[1,0]
	v_cvt_pk_bf16_f32 v6, v6, v7
	v_cvt_pk_bf16_f32 v7, v8, v9
	v_cvt_pk_bf16_f32 v8, v10, v11
	v_cvt_pk_bf16_f32 v9, v12, v13
	v_cvt_pk_bf16_f32 v10, v14, v15
	v_cvt_pk_bf16_f32 v11, v16, v17
	v_cvt_pk_bf16_f32 v12, v18, v19
	v_cvt_pk_bf16_f32 v13, v4, v5
	global_store_dwordx2 v[2:3], v[6:7], off
	global_store_dwordx2 v[2:3], v[8:9], off offset:32
	global_store_dwordx2 v[2:3], v[10:11], off offset:64
	global_store_dwordx2 v[2:3], v[12:13], off offset:96
.LBB0_996:
	s_or_b64 exec, exec, s[34:35]
	v_cmp_lt_i32_e32 vcc, -1, v22
	s_and_saveexec_b64 s[34:35], vcc
	s_cbranch_execz .LBB0_998
	v_mov_b32_e32 v2, v22
	v_mov_b32_e32 v3, v131
	v_lshlrev_b64 v[2:3], 12, v[2:3]
	v_mov_b32_e32 v1, v131
	v_lshl_add_u64 v[2:3], s[0:1], 0, v[2:3]
	v_lshl_add_u64 v[2:3], v[2:3], 0, v[0:1]
	v_mov_b32_e32 v4, v26
	v_pk_mul_f32 v[6:7], v[92:93], v[4:5] op_sel_hi:[1,0]
	v_pk_mul_f32 v[8:9], v[94:95], v[4:5] op_sel_hi:[1,0]
	v_pk_mul_f32 v[10:11], v[88:89], v[4:5] op_sel_hi:[1,0]
	v_pk_mul_f32 v[12:13], v[90:91], v[4:5] op_sel_hi:[1,0]
	v_pk_mul_f32 v[14:15], v[84:85], v[4:5] op_sel_hi:[1,0]
	v_pk_mul_f32 v[16:17], v[86:87], v[4:5] op_sel_hi:[1,0]
	v_pk_mul_f32 v[18:19], v[80:81], v[4:5] op_sel_hi:[1,0]
	v_pk_mul_f32 v[4:5], v[82:83], v[4:5] op_sel_hi:[1,0]
	v_cvt_pk_bf16_f32 v6, v6, v7
	v_cvt_pk_bf16_f32 v7, v8, v9
	v_cvt_pk_bf16_f32 v8, v10, v11
	v_cvt_pk_bf16_f32 v9, v12, v13
	v_cvt_pk_bf16_f32 v10, v14, v15
	v_cvt_pk_bf16_f32 v11, v16, v17
	v_cvt_pk_bf16_f32 v12, v18, v19
	v_cvt_pk_bf16_f32 v13, v4, v5
	global_store_dwordx2 v[2:3], v[6:7], off
	global_store_dwordx2 v[2:3], v[8:9], off offset:32
	global_store_dwordx2 v[2:3], v[10:11], off offset:64
	global_store_dwordx2 v[2:3], v[12:13], off offset:96
.LBB0_998:
	s_or_b64 exec, exec, s[34:35]
	v_cmp_lt_i32_e32 vcc, -1, v23
	s_and_saveexec_b64 s[34:35], vcc
	s_cbranch_execz .LBB0_968
	v_mov_b32_e32 v2, v23
	v_mov_b32_e32 v3, v131
	v_lshlrev_b64 v[2:3], 12, v[2:3]
	v_mov_b32_e32 v1, v131
	v_lshl_add_u64 v[2:3], s[0:1], 0, v[2:3]
	v_lshl_add_u64 v[0:1], v[2:3], 0, v[0:1]
	v_mov_b32_e32 v4, v27
	v_pk_mul_f32 v[2:3], v[68:69], v[4:5] op_sel_hi:[1,0]
	v_pk_mul_f32 v[6:7], v[70:71], v[4:5] op_sel_hi:[1,0]
	v_pk_mul_f32 v[8:9], v[64:65], v[4:5] op_sel_hi:[1,0]
	v_pk_mul_f32 v[10:11], v[66:67], v[4:5] op_sel_hi:[1,0]
	v_pk_mul_f32 v[12:13], v[76:77], v[4:5] op_sel_hi:[1,0]
	v_pk_mul_f32 v[14:15], v[78:79], v[4:5] op_sel_hi:[1,0]
	v_pk_mul_f32 v[16:17], v[72:73], v[4:5] op_sel_hi:[1,0]
	v_pk_mul_f32 v[4:5], v[74:75], v[4:5] op_sel_hi:[1,0]
	v_cvt_pk_bf16_f32 v2, v2, v3
	v_cvt_pk_bf16_f32 v3, v6, v7
	v_cvt_pk_bf16_f32 v6, v8, v9
	v_cvt_pk_bf16_f32 v7, v10, v11
	v_cvt_pk_bf16_f32 v8, v12, v13
	v_cvt_pk_bf16_f32 v9, v14, v15
	v_cvt_pk_bf16_f32 v10, v16, v17
	v_cvt_pk_bf16_f32 v11, v4, v5
	global_store_dwordx2 v[0:1], v[2:3], off
	global_store_dwordx2 v[0:1], v[6:7], off offset:32
	global_store_dwordx2 v[0:1], v[8:9], off offset:64
	global_store_dwordx2 v[0:1], v[10:11], off offset:96
	s_branch .LBB0_968
